# P4 + P6' epilogues de-serialised (tile/statistics loads in flight together, counted waits)
# speedup vs baseline: 1.0084x; 1.0041x over previous
.LBB0_677:
	s_lshl_b32 s3, s2, 8
	s_add_i32 s3, s3, s77
	v_add_u32_e32 v181, s3, v172
	v_lshl_add_u32 v185, v173, 3, s44
	v_lshlrev_b32_e32 v253, 2, v181
	v_lshlrev_b32_e32 v252, 2, v185
	v_lshlrev_b32_e32 v187, 12, v181
	v_lshl_add_u32 v187, v185, 1, v187
	v_lshlrev_b32_e32 v181, 13, v181
	v_lshl_add_u32 v185, v185, 2, v181
	global_load_dword v164, v253, s[12:13]
	global_load_dword v165, v253, s[12:13] offset:64
	global_load_dword v166, v253, s[12:13] offset:128
	global_load_dword v167, v253, s[12:13] offset:192
	global_load_dword v168, v253, s[12:13] offset:512
	global_load_dword v169, v253, s[12:13] offset:576
	global_load_dword v170, v253, s[12:13] offset:640
	global_load_dword v171, v253, s[12:13] offset:704
	global_load_dwordx4 v[148:151], v252, s[14:15] offset:0
	global_load_dwordx4 v[152:155], v252, s[14:15] offset:16
	global_load_dwordx4 v[156:159], v252, s[14:15] offset:512
	global_load_dwordx4 v[160:163], v252, s[14:15] offset:528
	s_mov_b32 s98, s18
	s_mov_b32 s99, s19
	s_nop 0
	global_load_dwordx4 v[188:191], v187, s[98:99]
	global_load_dwordx4 v[192:195], v187, s[98:99] offset:256
	s_add_u32 s98, s18, 0x10000
	s_addc_u32 s99, s19, 0
	s_nop 0
	global_load_dwordx4 v[196:199], v187, s[98:99]
	global_load_dwordx4 v[200:203], v187, s[98:99] offset:256
	s_add_u32 s98, s18, 0x20000
	s_addc_u32 s99, s19, 0
	s_nop 0
	global_load_dwordx4 v[204:207], v187, s[98:99]
	global_load_dwordx4 v[208:211], v187, s[98:99] offset:256
	s_add_u32 s98, s18, 0x30000
	s_addc_u32 s99, s19, 0
	s_nop 0
	global_load_dwordx4 v[212:215], v187, s[98:99]
	global_load_dwordx4 v[216:219], v187, s[98:99] offset:256
	s_add_u32 s98, s18, 0x80000
	s_addc_u32 s99, s19, 0
	s_nop 0
	global_load_dwordx4 v[220:223], v187, s[98:99]
	global_load_dwordx4 v[224:227], v187, s[98:99] offset:256
	s_add_u32 s98, s18, 0x90000
	s_addc_u32 s99, s19, 0
	s_nop 0
	global_load_dwordx4 v[228:231], v187, s[98:99]
	global_load_dwordx4 v[232:235], v187, s[98:99] offset:256
	s_add_u32 s98, s18, 0xa0000
	s_addc_u32 s99, s19, 0
	s_nop 0
	global_load_dwordx4 v[236:239], v187, s[98:99]
	global_load_dwordx4 v[240:243], v187, s[98:99] offset:256
	s_add_u32 s98, s18, 0xb0000
	s_addc_u32 s99, s19, 0
	s_nop 0
	global_load_dwordx4 v[244:247], v187, s[98:99]
	global_load_dwordx4 v[248:251], v187, s[98:99] offset:256
	s_waitcnt vmcnt(15)
	v_fmamk_f32 v184, v164, 0x3a000000, v177
	v_rcp_f32_e32 v184, v184
	v_and_b32_e32 v129, 0xffff0000, v188
	v_lshlrev_b32_e32 v128, 16, v188
	v_and_b32_e32 v131, 0xffff0000, v189
	v_lshlrev_b32_e32 v130, 16, v189
	v_and_b32_e32 v133, 0xffff0000, v190
	v_lshlrev_b32_e32 v132, 16, v190
	v_and_b32_e32 v135, 0xffff0000, v191
	v_lshlrev_b32_e32 v134, 16, v191
	v_pk_mul_f32 v[128:129], v[148:149], v[128:129]
	v_pk_mul_f32 v[130:131], v[150:151], v[130:131]
	v_pk_mul_f32 v[132:133], v[152:153], v[132:133]
	v_pk_mul_f32 v[134:135], v[154:155], v[134:135]
	v_pk_fma_f32 v[124:125], v[124:125], v[184:185], v[128:129] op_sel_hi:[1,0,1]
	v_pk_fma_f32 v[126:127], v[126:127], v[184:185], v[130:131] op_sel_hi:[1,0,1]
	v_pk_fma_f32 v[120:121], v[120:121], v[184:185], v[132:133] op_sel_hi:[1,0,1]
	v_pk_fma_f32 v[122:123], v[122:123], v[184:185], v[134:135] op_sel_hi:[1,0,1]
	v_pk_mul_f32 v[182:183], v[124:125], v[124:125]
	v_pk_fma_f32 v[182:183], v[126:127], v[126:127], v[182:183]
	v_pk_fma_f32 v[182:183], v[120:121], v[120:121], v[182:183]
	v_pk_fma_f32 v[182:183], v[122:123], v[122:123], v[182:183]
	s_waitcnt vmcnt(14)
	v_and_b32_e32 v129, 0xffff0000, v192
	v_lshlrev_b32_e32 v128, 16, v192
	v_and_b32_e32 v131, 0xffff0000, v193
	v_lshlrev_b32_e32 v130, 16, v193
	v_and_b32_e32 v133, 0xffff0000, v194
	v_lshlrev_b32_e32 v132, 16, v194
	v_and_b32_e32 v135, 0xffff0000, v195
	v_lshlrev_b32_e32 v134, 16, v195
	v_pk_mul_f32 v[128:129], v[156:157], v[128:129]
	v_pk_mul_f32 v[130:131], v[158:159], v[130:131]
	v_pk_mul_f32 v[132:133], v[160:161], v[132:133]
	v_pk_mul_f32 v[134:135], v[162:163], v[134:135]
	v_pk_fma_f32 v[116:117], v[116:117], v[184:185], v[128:129] op_sel_hi:[1,0,1]
	v_pk_fma_f32 v[118:119], v[118:119], v[184:185], v[130:131] op_sel_hi:[1,0,1]
	v_pk_fma_f32 v[112:113], v[112:113], v[184:185], v[132:133] op_sel_hi:[1,0,1]
	v_pk_fma_f32 v[114:115], v[114:115], v[184:185], v[134:135] op_sel_hi:[1,0,1]
	v_pk_fma_f32 v[182:183], v[116:117], v[116:117], v[182:183]
	v_pk_fma_f32 v[182:183], v[118:119], v[118:119], v[182:183]
	v_pk_fma_f32 v[182:183], v[112:113], v[112:113], v[182:183]
	v_pk_fma_f32 v[182:183], v[114:115], v[114:115], v[182:183]
	v_add_f32_e32 v164, v182, v183
	s_waitcnt vmcnt(13)
	v_fmamk_f32 v184, v165, 0x3a000000, v177
	v_rcp_f32_e32 v184, v184
	v_and_b32_e32 v129, 0xffff0000, v196
	v_lshlrev_b32_e32 v128, 16, v196
	v_and_b32_e32 v131, 0xffff0000, v197
	v_lshlrev_b32_e32 v130, 16, v197
	v_and_b32_e32 v133, 0xffff0000, v198
	v_lshlrev_b32_e32 v132, 16, v198
	v_and_b32_e32 v135, 0xffff0000, v199
	v_lshlrev_b32_e32 v134, 16, v199
	v_pk_mul_f32 v[128:129], v[148:149], v[128:129]
	v_pk_mul_f32 v[130:131], v[150:151], v[130:131]
	v_pk_mul_f32 v[132:133], v[152:153], v[132:133]
	v_pk_mul_f32 v[134:135], v[154:155], v[134:135]
	v_pk_fma_f32 v[108:109], v[108:109], v[184:185], v[128:129] op_sel_hi:[1,0,1]
	v_pk_fma_f32 v[110:111], v[110:111], v[184:185], v[130:131] op_sel_hi:[1,0,1]
	v_pk_fma_f32 v[104:105], v[104:105], v[184:185], v[132:133] op_sel_hi:[1,0,1]
	v_pk_fma_f32 v[106:107], v[106:107], v[184:185], v[134:135] op_sel_hi:[1,0,1]
	v_pk_mul_f32 v[182:183], v[108:109], v[108:109]
	v_pk_fma_f32 v[182:183], v[110:111], v[110:111], v[182:183]
	v_pk_fma_f32 v[182:183], v[104:105], v[104:105], v[182:183]
	v_pk_fma_f32 v[182:183], v[106:107], v[106:107], v[182:183]
	s_waitcnt vmcnt(12)
	v_and_b32_e32 v129, 0xffff0000, v200
	v_lshlrev_b32_e32 v128, 16, v200
	v_and_b32_e32 v131, 0xffff0000, v201
	v_lshlrev_b32_e32 v130, 16, v201
	v_and_b32_e32 v133, 0xffff0000, v202
	v_lshlrev_b32_e32 v132, 16, v202
	v_and_b32_e32 v135, 0xffff0000, v203
	v_lshlrev_b32_e32 v134, 16, v203
	v_pk_mul_f32 v[128:129], v[156:157], v[128:129]
	v_pk_mul_f32 v[130:131], v[158:159], v[130:131]
	v_pk_mul_f32 v[132:133], v[160:161], v[132:133]
	v_pk_mul_f32 v[134:135], v[162:163], v[134:135]
	v_pk_fma_f32 v[100:101], v[100:101], v[184:185], v[128:129] op_sel_hi:[1,0,1]
	v_pk_fma_f32 v[102:103], v[102:103], v[184:185], v[130:131] op_sel_hi:[1,0,1]
	v_pk_fma_f32 v[96:97], v[96:97], v[184:185], v[132:133] op_sel_hi:[1,0,1]
	v_pk_fma_f32 v[98:99], v[98:99], v[184:185], v[134:135] op_sel_hi:[1,0,1]
	v_pk_fma_f32 v[182:183], v[100:101], v[100:101], v[182:183]
	v_pk_fma_f32 v[182:183], v[102:103], v[102:103], v[182:183]
	v_pk_fma_f32 v[182:183], v[96:97], v[96:97], v[182:183]
	v_pk_fma_f32 v[182:183], v[98:99], v[98:99], v[182:183]
	v_add_f32_e32 v165, v182, v183
	s_waitcnt vmcnt(11)
	v_fmamk_f32 v184, v166, 0x3a000000, v177
	v_rcp_f32_e32 v184, v184
	v_and_b32_e32 v129, 0xffff0000, v204
	v_lshlrev_b32_e32 v128, 16, v204
	v_and_b32_e32 v131, 0xffff0000, v205
	v_lshlrev_b32_e32 v130, 16, v205
	v_and_b32_e32 v133, 0xffff0000, v206
	v_lshlrev_b32_e32 v132, 16, v206
	v_and_b32_e32 v135, 0xffff0000, v207
	v_lshlrev_b32_e32 v134, 16, v207
	v_pk_mul_f32 v[128:129], v[148:149], v[128:129]
	v_pk_mul_f32 v[130:131], v[150:151], v[130:131]
	v_pk_mul_f32 v[132:133], v[152:153], v[132:133]
	v_pk_mul_f32 v[134:135], v[154:155], v[134:135]
	v_pk_fma_f32 v[92:93], v[92:93], v[184:185], v[128:129] op_sel_hi:[1,0,1]
	v_pk_fma_f32 v[94:95], v[94:95], v[184:185], v[130:131] op_sel_hi:[1,0,1]
	v_pk_fma_f32 v[88:89], v[88:89], v[184:185], v[132:133] op_sel_hi:[1,0,1]
	v_pk_fma_f32 v[90:91], v[90:91], v[184:185], v[134:135] op_sel_hi:[1,0,1]
	v_pk_mul_f32 v[182:183], v[92:93], v[92:93]
	v_pk_fma_f32 v[182:183], v[94:95], v[94:95], v[182:183]
	v_pk_fma_f32 v[182:183], v[88:89], v[88:89], v[182:183]
	v_pk_fma_f32 v[182:183], v[90:91], v[90:91], v[182:183]
	s_waitcnt vmcnt(10)
	v_and_b32_e32 v129, 0xffff0000, v208
	v_lshlrev_b32_e32 v128, 16, v208
	v_and_b32_e32 v131, 0xffff0000, v209
	v_lshlrev_b32_e32 v130, 16, v209
	v_and_b32_e32 v133, 0xffff0000, v210
	v_lshlrev_b32_e32 v132, 16, v210
	v_and_b32_e32 v135, 0xffff0000, v211
	v_lshlrev_b32_e32 v134, 16, v211
	v_pk_mul_f32 v[128:129], v[156:157], v[128:129]
	v_pk_mul_f32 v[130:131], v[158:159], v[130:131]
	v_pk_mul_f32 v[132:133], v[160:161], v[132:133]
	v_pk_mul_f32 v[134:135], v[162:163], v[134:135]
	v_pk_fma_f32 v[84:85], v[84:85], v[184:185], v[128:129] op_sel_hi:[1,0,1]
	v_pk_fma_f32 v[86:87], v[86:87], v[184:185], v[130:131] op_sel_hi:[1,0,1]
	v_pk_fma_f32 v[80:81], v[80:81], v[184:185], v[132:133] op_sel_hi:[1,0,1]
	v_pk_fma_f32 v[82:83], v[82:83], v[184:185], v[134:135] op_sel_hi:[1,0,1]
	v_pk_fma_f32 v[182:183], v[84:85], v[84:85], v[182:183]
	v_pk_fma_f32 v[182:183], v[86:87], v[86:87], v[182:183]
	v_pk_fma_f32 v[182:183], v[80:81], v[80:81], v[182:183]
	v_pk_fma_f32 v[182:183], v[82:83], v[82:83], v[182:183]
	v_add_f32_e32 v166, v182, v183
	s_waitcnt vmcnt(9)
	v_fmamk_f32 v184, v167, 0x3a000000, v177
	v_rcp_f32_e32 v184, v184
	v_and_b32_e32 v129, 0xffff0000, v212
	v_lshlrev_b32_e32 v128, 16, v212
	v_and_b32_e32 v131, 0xffff0000, v213
	v_lshlrev_b32_e32 v130, 16, v213
	v_and_b32_e32 v133, 0xffff0000, v214
	v_lshlrev_b32_e32 v132, 16, v214
	v_and_b32_e32 v135, 0xffff0000, v215
	v_lshlrev_b32_e32 v134, 16, v215
	v_pk_mul_f32 v[128:129], v[148:149], v[128:129]
	v_pk_mul_f32 v[130:131], v[150:151], v[130:131]
	v_pk_mul_f32 v[132:133], v[152:153], v[132:133]
	v_pk_mul_f32 v[134:135], v[154:155], v[134:135]
	v_pk_fma_f32 v[76:77], v[76:77], v[184:185], v[128:129] op_sel_hi:[1,0,1]
	v_pk_fma_f32 v[78:79], v[78:79], v[184:185], v[130:131] op_sel_hi:[1,0,1]
	v_pk_fma_f32 v[72:73], v[72:73], v[184:185], v[132:133] op_sel_hi:[1,0,1]
	v_pk_fma_f32 v[74:75], v[74:75], v[184:185], v[134:135] op_sel_hi:[1,0,1]
	v_pk_mul_f32 v[182:183], v[76:77], v[76:77]
	v_pk_fma_f32 v[182:183], v[78:79], v[78:79], v[182:183]
	v_pk_fma_f32 v[182:183], v[72:73], v[72:73], v[182:183]
	v_pk_fma_f32 v[182:183], v[74:75], v[74:75], v[182:183]
	s_waitcnt vmcnt(8)
	v_and_b32_e32 v129, 0xffff0000, v216
	v_lshlrev_b32_e32 v128, 16, v216
	v_and_b32_e32 v131, 0xffff0000, v217
	v_lshlrev_b32_e32 v130, 16, v217
	v_and_b32_e32 v133, 0xffff0000, v218
	v_lshlrev_b32_e32 v132, 16, v218
	v_and_b32_e32 v135, 0xffff0000, v219
	v_lshlrev_b32_e32 v134, 16, v219
	v_pk_mul_f32 v[128:129], v[156:157], v[128:129]
	v_pk_mul_f32 v[130:131], v[158:159], v[130:131]
	v_pk_mul_f32 v[132:133], v[160:161], v[132:133]
	v_pk_mul_f32 v[134:135], v[162:163], v[134:135]
	v_pk_fma_f32 v[68:69], v[68:69], v[184:185], v[128:129] op_sel_hi:[1,0,1]
	v_pk_fma_f32 v[70:71], v[70:71], v[184:185], v[130:131] op_sel_hi:[1,0,1]
	v_pk_fma_f32 v[64:65], v[64:65], v[184:185], v[132:133] op_sel_hi:[1,0,1]
	v_pk_fma_f32 v[66:67], v[66:67], v[184:185], v[134:135] op_sel_hi:[1,0,1]
	v_pk_fma_f32 v[182:183], v[68:69], v[68:69], v[182:183]
	v_pk_fma_f32 v[182:183], v[70:71], v[70:71], v[182:183]
	v_pk_fma_f32 v[182:183], v[64:65], v[64:65], v[182:183]
	v_pk_fma_f32 v[182:183], v[66:67], v[66:67], v[182:183]
	v_add_f32_e32 v167, v182, v183
	s_waitcnt vmcnt(7)
	v_fmamk_f32 v184, v168, 0x3a000000, v177
	v_rcp_f32_e32 v184, v184
	v_and_b32_e32 v129, 0xffff0000, v220
	v_lshlrev_b32_e32 v128, 16, v220
	v_and_b32_e32 v131, 0xffff0000, v221
	v_lshlrev_b32_e32 v130, 16, v221
	v_and_b32_e32 v133, 0xffff0000, v222
	v_lshlrev_b32_e32 v132, 16, v222
	v_and_b32_e32 v135, 0xffff0000, v223
	v_lshlrev_b32_e32 v134, 16, v223
	v_pk_mul_f32 v[128:129], v[148:149], v[128:129]
	v_pk_mul_f32 v[130:131], v[150:151], v[130:131]
	v_pk_mul_f32 v[132:133], v[152:153], v[132:133]
	v_pk_mul_f32 v[134:135], v[154:155], v[134:135]
	v_pk_fma_f32 v[60:61], v[60:61], v[184:185], v[128:129] op_sel_hi:[1,0,1]
	v_pk_fma_f32 v[62:63], v[62:63], v[184:185], v[130:131] op_sel_hi:[1,0,1]
	v_pk_fma_f32 v[56:57], v[56:57], v[184:185], v[132:133] op_sel_hi:[1,0,1]
	v_pk_fma_f32 v[58:59], v[58:59], v[184:185], v[134:135] op_sel_hi:[1,0,1]
	v_pk_mul_f32 v[182:183], v[60:61], v[60:61]
	v_pk_fma_f32 v[182:183], v[62:63], v[62:63], v[182:183]
	v_pk_fma_f32 v[182:183], v[56:57], v[56:57], v[182:183]
	v_pk_fma_f32 v[182:183], v[58:59], v[58:59], v[182:183]
	s_waitcnt vmcnt(6)
	v_and_b32_e32 v129, 0xffff0000, v224
	v_lshlrev_b32_e32 v128, 16, v224
	v_and_b32_e32 v131, 0xffff0000, v225
	v_lshlrev_b32_e32 v130, 16, v225
	v_and_b32_e32 v133, 0xffff0000, v226
	v_lshlrev_b32_e32 v132, 16, v226
	v_and_b32_e32 v135, 0xffff0000, v227
	v_lshlrev_b32_e32 v134, 16, v227
	v_pk_mul_f32 v[128:129], v[156:157], v[128:129]
	v_pk_mul_f32 v[130:131], v[158:159], v[130:131]
	v_pk_mul_f32 v[132:133], v[160:161], v[132:133]
	v_pk_mul_f32 v[134:135], v[162:163], v[134:135]
	v_pk_fma_f32 v[52:53], v[52:53], v[184:185], v[128:129] op_sel_hi:[1,0,1]
	v_pk_fma_f32 v[54:55], v[54:55], v[184:185], v[130:131] op_sel_hi:[1,0,1]
	v_pk_fma_f32 v[48:49], v[48:49], v[184:185], v[132:133] op_sel_hi:[1,0,1]
	v_pk_fma_f32 v[50:51], v[50:51], v[184:185], v[134:135] op_sel_hi:[1,0,1]
	v_pk_fma_f32 v[182:183], v[52:53], v[52:53], v[182:183]
	v_pk_fma_f32 v[182:183], v[54:55], v[54:55], v[182:183]
	v_pk_fma_f32 v[182:183], v[48:49], v[48:49], v[182:183]
	v_pk_fma_f32 v[182:183], v[50:51], v[50:51], v[182:183]
	v_add_f32_e32 v168, v182, v183
	s_waitcnt vmcnt(5)
	v_fmamk_f32 v184, v169, 0x3a000000, v177
	v_rcp_f32_e32 v184, v184
	v_and_b32_e32 v129, 0xffff0000, v228
	v_lshlrev_b32_e32 v128, 16, v228
	v_and_b32_e32 v131, 0xffff0000, v229
	v_lshlrev_b32_e32 v130, 16, v229
	v_and_b32_e32 v133, 0xffff0000, v230
	v_lshlrev_b32_e32 v132, 16, v230
	v_and_b32_e32 v135, 0xffff0000, v231
	v_lshlrev_b32_e32 v134, 16, v231
	v_pk_mul_f32 v[128:129], v[148:149], v[128:129]
	v_pk_mul_f32 v[130:131], v[150:151], v[130:131]
	v_pk_mul_f32 v[132:133], v[152:153], v[132:133]
	v_pk_mul_f32 v[134:135], v[154:155], v[134:135]
	v_pk_fma_f32 v[44:45], v[44:45], v[184:185], v[128:129] op_sel_hi:[1,0,1]
	v_pk_fma_f32 v[46:47], v[46:47], v[184:185], v[130:131] op_sel_hi:[1,0,1]
	v_pk_fma_f32 v[40:41], v[40:41], v[184:185], v[132:133] op_sel_hi:[1,0,1]
	v_pk_fma_f32 v[42:43], v[42:43], v[184:185], v[134:135] op_sel_hi:[1,0,1]
	v_pk_mul_f32 v[182:183], v[44:45], v[44:45]
	v_pk_fma_f32 v[182:183], v[46:47], v[46:47], v[182:183]
	v_pk_fma_f32 v[182:183], v[40:41], v[40:41], v[182:183]
	v_pk_fma_f32 v[182:183], v[42:43], v[42:43], v[182:183]
	s_waitcnt vmcnt(4)
	v_and_b32_e32 v129, 0xffff0000, v232
	v_lshlrev_b32_e32 v128, 16, v232
	v_and_b32_e32 v131, 0xffff0000, v233
	v_lshlrev_b32_e32 v130, 16, v233
	v_and_b32_e32 v133, 0xffff0000, v234
	v_lshlrev_b32_e32 v132, 16, v234
	v_and_b32_e32 v135, 0xffff0000, v235
	v_lshlrev_b32_e32 v134, 16, v235
	v_pk_mul_f32 v[128:129], v[156:157], v[128:129]
	v_pk_mul_f32 v[130:131], v[158:159], v[130:131]
	v_pk_mul_f32 v[132:133], v[160:161], v[132:133]
	v_pk_mul_f32 v[134:135], v[162:163], v[134:135]
	v_pk_fma_f32 v[36:37], v[36:37], v[184:185], v[128:129] op_sel_hi:[1,0,1]
	v_pk_fma_f32 v[38:39], v[38:39], v[184:185], v[130:131] op_sel_hi:[1,0,1]
	v_pk_fma_f32 v[32:33], v[32:33], v[184:185], v[132:133] op_sel_hi:[1,0,1]
	v_pk_fma_f32 v[34:35], v[34:35], v[184:185], v[134:135] op_sel_hi:[1,0,1]
	v_pk_fma_f32 v[182:183], v[36:37], v[36:37], v[182:183]
	v_pk_fma_f32 v[182:183], v[38:39], v[38:39], v[182:183]
	v_pk_fma_f32 v[182:183], v[32:33], v[32:33], v[182:183]
	v_pk_fma_f32 v[182:183], v[34:35], v[34:35], v[182:183]
	v_add_f32_e32 v169, v182, v183
	s_waitcnt vmcnt(3)
	v_fmamk_f32 v184, v170, 0x3a000000, v177
	v_rcp_f32_e32 v184, v184
	v_and_b32_e32 v129, 0xffff0000, v236
	v_lshlrev_b32_e32 v128, 16, v236
	v_and_b32_e32 v131, 0xffff0000, v237
	v_lshlrev_b32_e32 v130, 16, v237
	v_and_b32_e32 v133, 0xffff0000, v238
	v_lshlrev_b32_e32 v132, 16, v238
	v_and_b32_e32 v135, 0xffff0000, v239
	v_lshlrev_b32_e32 v134, 16, v239
	v_pk_mul_f32 v[128:129], v[148:149], v[128:129]
	v_pk_mul_f32 v[130:131], v[150:151], v[130:131]
	v_pk_mul_f32 v[132:133], v[152:153], v[132:133]
	v_pk_mul_f32 v[134:135], v[154:155], v[134:135]
	v_pk_fma_f32 v[28:29], v[28:29], v[184:185], v[128:129] op_sel_hi:[1,0,1]
	v_pk_fma_f32 v[30:31], v[30:31], v[184:185], v[130:131] op_sel_hi:[1,0,1]
	v_pk_fma_f32 v[24:25], v[24:25], v[184:185], v[132:133] op_sel_hi:[1,0,1]
	v_pk_fma_f32 v[26:27], v[26:27], v[184:185], v[134:135] op_sel_hi:[1,0,1]
	v_pk_mul_f32 v[182:183], v[28:29], v[28:29]
	v_pk_fma_f32 v[182:183], v[30:31], v[30:31], v[182:183]
	v_pk_fma_f32 v[182:183], v[24:25], v[24:25], v[182:183]
	v_pk_fma_f32 v[182:183], v[26:27], v[26:27], v[182:183]
	s_waitcnt vmcnt(2)
	v_and_b32_e32 v129, 0xffff0000, v240
	v_lshlrev_b32_e32 v128, 16, v240
	v_and_b32_e32 v131, 0xffff0000, v241
	v_lshlrev_b32_e32 v130, 16, v241
	v_and_b32_e32 v133, 0xffff0000, v242
	v_lshlrev_b32_e32 v132, 16, v242
	v_and_b32_e32 v135, 0xffff0000, v243
	v_lshlrev_b32_e32 v134, 16, v243
	v_pk_mul_f32 v[128:129], v[156:157], v[128:129]
	v_pk_mul_f32 v[130:131], v[158:159], v[130:131]
	v_pk_mul_f32 v[132:133], v[160:161], v[132:133]
	v_pk_mul_f32 v[134:135], v[162:163], v[134:135]
	v_pk_fma_f32 v[20:21], v[20:21], v[184:185], v[128:129] op_sel_hi:[1,0,1]
	v_pk_fma_f32 v[22:23], v[22:23], v[184:185], v[130:131] op_sel_hi:[1,0,1]
	v_pk_fma_f32 v[16:17], v[16:17], v[184:185], v[132:133] op_sel_hi:[1,0,1]
	v_pk_fma_f32 v[18:19], v[18:19], v[184:185], v[134:135] op_sel_hi:[1,0,1]
	v_pk_fma_f32 v[182:183], v[20:21], v[20:21], v[182:183]
	v_pk_fma_f32 v[182:183], v[22:23], v[22:23], v[182:183]
	v_pk_fma_f32 v[182:183], v[16:17], v[16:17], v[182:183]
	v_pk_fma_f32 v[182:183], v[18:19], v[18:19], v[182:183]
	v_add_f32_e32 v170, v182, v183
	s_waitcnt vmcnt(1)
	v_fmamk_f32 v184, v171, 0x3a000000, v177
	v_rcp_f32_e32 v184, v184
	v_and_b32_e32 v129, 0xffff0000, v244
	v_lshlrev_b32_e32 v128, 16, v244
	v_and_b32_e32 v131, 0xffff0000, v245
	v_lshlrev_b32_e32 v130, 16, v245
	v_and_b32_e32 v133, 0xffff0000, v246
	v_lshlrev_b32_e32 v132, 16, v246
	v_and_b32_e32 v135, 0xffff0000, v247
	v_lshlrev_b32_e32 v134, 16, v247
	v_pk_mul_f32 v[128:129], v[148:149], v[128:129]
	v_pk_mul_f32 v[130:131], v[150:151], v[130:131]
	v_pk_mul_f32 v[132:133], v[152:153], v[132:133]
	v_pk_mul_f32 v[134:135], v[154:155], v[134:135]
	v_pk_fma_f32 v[12:13], v[12:13], v[184:185], v[128:129] op_sel_hi:[1,0,1]
	v_pk_fma_f32 v[14:15], v[14:15], v[184:185], v[130:131] op_sel_hi:[1,0,1]
	v_pk_fma_f32 v[8:9], v[8:9], v[184:185], v[132:133] op_sel_hi:[1,0,1]
	v_pk_fma_f32 v[10:11], v[10:11], v[184:185], v[134:135] op_sel_hi:[1,0,1]
	v_pk_mul_f32 v[182:183], v[12:13], v[12:13]
	v_pk_fma_f32 v[182:183], v[14:15], v[14:15], v[182:183]
	v_pk_fma_f32 v[182:183], v[8:9], v[8:9], v[182:183]
	v_pk_fma_f32 v[182:183], v[10:11], v[10:11], v[182:183]
	s_waitcnt vmcnt(0)
	v_and_b32_e32 v129, 0xffff0000, v248
	v_lshlrev_b32_e32 v128, 16, v248
	v_and_b32_e32 v131, 0xffff0000, v249
	v_lshlrev_b32_e32 v130, 16, v249
	v_and_b32_e32 v133, 0xffff0000, v250
	v_lshlrev_b32_e32 v132, 16, v250
	v_and_b32_e32 v135, 0xffff0000, v251
	v_lshlrev_b32_e32 v134, 16, v251
	v_pk_mul_f32 v[128:129], v[156:157], v[128:129]
	v_pk_mul_f32 v[130:131], v[158:159], v[130:131]
	v_pk_mul_f32 v[132:133], v[160:161], v[132:133]
	v_pk_mul_f32 v[134:135], v[162:163], v[134:135]
	v_pk_fma_f32 v[4:5], v[4:5], v[184:185], v[128:129] op_sel_hi:[1,0,1]
	v_pk_fma_f32 v[6:7], v[6:7], v[184:185], v[130:131] op_sel_hi:[1,0,1]
	v_pk_fma_f32 v[0:1], v[0:1], v[184:185], v[132:133] op_sel_hi:[1,0,1]
	v_pk_fma_f32 v[2:3], v[2:3], v[184:185], v[134:135] op_sel_hi:[1,0,1]
	v_pk_fma_f32 v[182:183], v[4:5], v[4:5], v[182:183]
	v_pk_fma_f32 v[182:183], v[6:7], v[6:7], v[182:183]
	v_pk_fma_f32 v[182:183], v[0:1], v[0:1], v[182:183]
	v_pk_fma_f32 v[182:183], v[2:3], v[2:3], v[182:183]
	v_add_f32_e32 v171, v182, v183
	v_xor_b32_e32 v128, 16, v186
	v_xor_b32_e32 v129, 32, v186
	v_lshlrev_b32_e32 v128, 2, v128
	v_lshlrev_b32_e32 v129, 2, v129
	ds_bpermute_b32 v188, v128, v164
	ds_bpermute_b32 v189, v128, v165
	ds_bpermute_b32 v190, v128, v166
	ds_bpermute_b32 v191, v128, v167
	ds_bpermute_b32 v192, v128, v168
	ds_bpermute_b32 v193, v128, v169
	ds_bpermute_b32 v194, v128, v170
	ds_bpermute_b32 v195, v128, v171
	s_waitcnt lgkmcnt(7)
	v_add_f32_e32 v164, v164, v188
	s_waitcnt lgkmcnt(6)
	v_add_f32_e32 v165, v165, v189
	s_waitcnt lgkmcnt(5)
	v_add_f32_e32 v166, v166, v190
	s_waitcnt lgkmcnt(4)
	v_add_f32_e32 v167, v167, v191
	s_waitcnt lgkmcnt(3)
	v_add_f32_e32 v168, v168, v192
	s_waitcnt lgkmcnt(2)
	v_add_f32_e32 v169, v169, v193
	s_waitcnt lgkmcnt(1)
	v_add_f32_e32 v170, v170, v194
	s_waitcnt lgkmcnt(0)
	v_add_f32_e32 v171, v171, v195
	ds_bpermute_b32 v188, v129, v164
	ds_bpermute_b32 v189, v129, v165
	ds_bpermute_b32 v190, v129, v166
	ds_bpermute_b32 v191, v129, v167
	ds_bpermute_b32 v192, v129, v168
	ds_bpermute_b32 v193, v129, v169
	ds_bpermute_b32 v194, v129, v170
	ds_bpermute_b32 v195, v129, v171
	v_cmp_eq_u32_e32 vcc, 0, v173
	s_and_saveexec_b64 s[36:37], vcc
	s_waitcnt lgkmcnt(7)
	v_add_f32_e32 v164, v164, v188
	global_atomic_add_f32 v253, v164, s[16:17]
	s_waitcnt lgkmcnt(6)
	v_add_f32_e32 v165, v165, v189
	global_atomic_add_f32 v253, v165, s[16:17] offset:64
	s_waitcnt lgkmcnt(5)
	v_add_f32_e32 v166, v166, v190
	global_atomic_add_f32 v253, v166, s[16:17] offset:128
	s_waitcnt lgkmcnt(4)
	v_add_f32_e32 v167, v167, v191
	global_atomic_add_f32 v253, v167, s[16:17] offset:192
	s_waitcnt lgkmcnt(3)
	v_add_f32_e32 v168, v168, v192
	global_atomic_add_f32 v253, v168, s[16:17] offset:512
	s_waitcnt lgkmcnt(2)
	v_add_f32_e32 v169, v169, v193
	global_atomic_add_f32 v253, v169, s[16:17] offset:576
	s_waitcnt lgkmcnt(1)
	v_add_f32_e32 v170, v170, v194
	global_atomic_add_f32 v253, v170, s[16:17] offset:640
	s_waitcnt lgkmcnt(0)
	v_add_f32_e32 v171, v171, v195
	global_atomic_add_f32 v253, v171, s[16:17] offset:704
	s_or_b64 exec, exec, s[36:37]
	s_lshl_b32 s2, s2, 6
	s_ashr_i32 s3, s2, 31
	s_lshl_b64 s[2:3], s[2:3], 2
	s_waitcnt vmcnt(0)
	s_add_u32 s24, s42, s2
	s_addc_u32 s25, s43, s3
	v_cmp_eq_u32_e32 vcc, 0, v173
	v_cmp_eq_u32_e64 s[2:3], 0, v172
	s_and_b64 s[30:31], s[2:3], vcc
	v_mov_b32_e32 v181, 1
	s_and_saveexec_b64 s[2:3], s[30:31]
	global_atomic_add v139, v181, s[24:25]
	s_or_b64 exec, exec, s[2:3]
	s_mov_b32 s29, 0x100001
	s_branch .Lp6_spin

.Lp6_spin:
	global_load_dword v181, v139, s[24:25] sc1
	s_waitcnt vmcnt(0)
	v_readfirstlane_b32 s2, v181
	s_cmp_gt_u32 s2, 63
	s_mov_b64 s[2:3], -1
	s_cbranch_scc1 .Lp6_spin_chk
	s_add_i32 s29, s29, -1
	s_cmp_eq_u32 s29, 0
	s_cselect_b64 s[2:3], -1, 0
	s_sleep 1
	s_branch .Lp6_spin_chk
.Lp6_part2:
	global_load_dword v164, v253, s[16:17] sc1
	global_load_dword v165, v253, s[16:17] offset:64 sc1
	global_load_dword v166, v253, s[16:17] offset:128 sc1
	global_load_dword v167, v253, s[16:17] offset:192 sc1
	global_load_dword v168, v253, s[16:17] offset:512 sc1
	global_load_dword v169, v253, s[16:17] offset:576 sc1
	global_load_dword v170, v253, s[16:17] offset:640 sc1
	global_load_dword v171, v253, s[16:17] offset:704 sc1
	global_load_dwordx4 v[148:151], v252, s[86:87] offset:0
	global_load_dwordx4 v[152:155], v252, s[86:87] offset:16
	global_load_dwordx4 v[156:159], v252, s[86:87] offset:512
	global_load_dwordx4 v[160:163], v252, s[86:87] offset:528
	s_waitcnt vmcnt(0)
	v_fmamk_f32 v128, v164, 0x3a000000, v177
	v_mul_f32_e32 v129, 0x4f800000, v128
	v_cmp_gt_f32_e32 vcc, s9, v128
	s_nop 1
	v_cndmask_b32_e32 v128, v128, v129, vcc
	v_sqrt_f32_e32 v129, v128
	s_nop 0
	v_add_u32_e32 v130, -1, v129
	v_add_u32_e32 v131, 1, v129
	v_fma_f32 v132, -v130, v129, v128
	v_fma_f32 v133, -v131, v129, v128
	v_cmp_ge_f32_e64 s[2:3], 0, v132
	s_nop 1
	v_cndmask_b32_e64 v129, v129, v130, s[2:3]
	v_cmp_lt_f32_e64 s[2:3], 0, v133
	s_nop 1
	v_cndmask_b32_e64 v129, v129, v131, s[2:3]
	v_mul_f32_e32 v130, 0x37800000, v129
	v_cndmask_b32_e32 v129, v129, v130, vcc
	v_cmp_class_f32_e32 vcc, v128, v178
	s_nop 1
	v_cndmask_b32_e32 v128, v129, v128, vcc
	v_div_scale_f32 v129, s[2:3], v128, v128, 1.0
	v_rcp_f32_e32 v130, v129
	v_div_scale_f32 v131, vcc, 1.0, v128, 1.0
	v_fma_f32 v132, -v129, v130, 1.0
	v_fmac_f32_e32 v130, v132, v130
	v_mul_f32_e32 v132, v131, v130
	v_fma_f32 v133, -v129, v132, v131
	v_fmac_f32_e32 v132, v133, v130
	v_fma_f32 v129, -v129, v132, v131
	v_div_fmas_f32 v129, v129, v130, v132
	v_div_fixup_f32 v184, v129, v128, 1.0
	s_mov_b32 s100, s64
	s_mov_b32 s101, s65
	v_pk_mul_f32 v[188:189], v[124:125], v[184:185] op_sel_hi:[1,0]
	v_pk_mul_f32 v[190:191], v[126:127], v[184:185] op_sel_hi:[1,0]
	v_pk_mul_f32 v[192:193], v[120:121], v[184:185] op_sel_hi:[1,0]
	v_pk_mul_f32 v[194:195], v[122:123], v[184:185] op_sel_hi:[1,0]
	v_pk_mul_f32 v[188:189], v[148:149], v[188:189]
	v_pk_mul_f32 v[190:191], v[150:151], v[190:191]
	v_pk_mul_f32 v[192:193], v[152:153], v[192:193]
	v_pk_mul_f32 v[194:195], v[154:155], v[194:195]
	s_nop 0
	global_store_dwordx4 v185, v[188:191], s[100:101] offset:0
	global_store_dwordx4 v185, v[192:195], s[100:101] offset:16
	v_pk_mul_f32 v[196:197], v[116:117], v[184:185] op_sel_hi:[1,0]
	v_pk_mul_f32 v[198:199], v[118:119], v[184:185] op_sel_hi:[1,0]
	v_pk_mul_f32 v[200:201], v[112:113], v[184:185] op_sel_hi:[1,0]
	v_pk_mul_f32 v[202:203], v[114:115], v[184:185] op_sel_hi:[1,0]
	v_pk_mul_f32 v[196:197], v[156:157], v[196:197]
	v_pk_mul_f32 v[198:199], v[158:159], v[198:199]
	v_pk_mul_f32 v[200:201], v[160:161], v[200:201]
	v_pk_mul_f32 v[202:203], v[162:163], v[202:203]
	s_nop 0
	global_store_dwordx4 v185, v[196:199], s[100:101] offset:512
	global_store_dwordx4 v185, v[200:203], s[100:101] offset:528
	s_waitcnt vmcnt(14)
	v_fmamk_f32 v128, v165, 0x3a000000, v177
	v_mul_f32_e32 v129, 0x4f800000, v128
	v_cmp_gt_f32_e32 vcc, s9, v128
	s_nop 1
	v_cndmask_b32_e32 v128, v128, v129, vcc
	v_sqrt_f32_e32 v129, v128
	s_nop 0
	v_add_u32_e32 v130, -1, v129
	v_add_u32_e32 v131, 1, v129
	v_fma_f32 v132, -v130, v129, v128
	v_fma_f32 v133, -v131, v129, v128
	v_cmp_ge_f32_e64 s[2:3], 0, v132
	s_nop 1
	v_cndmask_b32_e64 v129, v129, v130, s[2:3]
	v_cmp_lt_f32_e64 s[2:3], 0, v133
	s_nop 1
	v_cndmask_b32_e64 v129, v129, v131, s[2:3]
	v_mul_f32_e32 v130, 0x37800000, v129
	v_cndmask_b32_e32 v129, v129, v130, vcc
	v_cmp_class_f32_e32 vcc, v128, v178
	s_nop 1
	v_cndmask_b32_e32 v128, v129, v128, vcc
	v_div_scale_f32 v129, s[2:3], v128, v128, 1.0
	v_rcp_f32_e32 v130, v129
	v_div_scale_f32 v131, vcc, 1.0, v128, 1.0
	v_fma_f32 v132, -v129, v130, 1.0
	v_fmac_f32_e32 v130, v132, v130
	v_mul_f32_e32 v132, v131, v130
	v_fma_f32 v133, -v129, v132, v131
	v_fmac_f32_e32 v132, v133, v130
	v_fma_f32 v129, -v129, v132, v131
	v_div_fmas_f32 v129, v129, v130, v132
	v_div_fixup_f32 v184, v129, v128, 1.0
	s_add_u32 s100, s64, 0x20000
	s_addc_u32 s101, s65, 0
	v_pk_mul_f32 v[204:205], v[108:109], v[184:185] op_sel_hi:[1,0]
	v_pk_mul_f32 v[206:207], v[110:111], v[184:185] op_sel_hi:[1,0]
	v_pk_mul_f32 v[208:209], v[104:105], v[184:185] op_sel_hi:[1,0]
	v_pk_mul_f32 v[210:211], v[106:107], v[184:185] op_sel_hi:[1,0]
	v_pk_mul_f32 v[204:205], v[148:149], v[204:205]
	v_pk_mul_f32 v[206:207], v[150:151], v[206:207]
	v_pk_mul_f32 v[208:209], v[152:153], v[208:209]
	v_pk_mul_f32 v[210:211], v[154:155], v[210:211]
	s_nop 0
	global_store_dwordx4 v185, v[204:207], s[100:101] offset:0
	global_store_dwordx4 v185, v[208:211], s[100:101] offset:16
	v_pk_mul_f32 v[212:213], v[100:101], v[184:185] op_sel_hi:[1,0]
	v_pk_mul_f32 v[214:215], v[102:103], v[184:185] op_sel_hi:[1,0]
	v_pk_mul_f32 v[216:217], v[96:97], v[184:185] op_sel_hi:[1,0]
	v_pk_mul_f32 v[218:219], v[98:99], v[184:185] op_sel_hi:[1,0]
	v_pk_mul_f32 v[212:213], v[156:157], v[212:213]
	v_pk_mul_f32 v[214:215], v[158:159], v[214:215]
	v_pk_mul_f32 v[216:217], v[160:161], v[216:217]
	v_pk_mul_f32 v[218:219], v[162:163], v[218:219]
	s_nop 0
	global_store_dwordx4 v185, v[212:215], s[100:101] offset:512
	global_store_dwordx4 v185, v[216:219], s[100:101] offset:528
	s_waitcnt vmcnt(17)
	v_fmamk_f32 v128, v166, 0x3a000000, v177
	v_mul_f32_e32 v129, 0x4f800000, v128
	v_cmp_gt_f32_e32 vcc, s9, v128
	s_nop 1
	v_cndmask_b32_e32 v128, v128, v129, vcc
	v_sqrt_f32_e32 v129, v128
	s_nop 0
	v_add_u32_e32 v130, -1, v129
	v_add_u32_e32 v131, 1, v129
	v_fma_f32 v132, -v130, v129, v128
	v_fma_f32 v133, -v131, v129, v128
	v_cmp_ge_f32_e64 s[2:3], 0, v132
	s_nop 1
	v_cndmask_b32_e64 v129, v129, v130, s[2:3]
	v_cmp_lt_f32_e64 s[2:3], 0, v133
	s_nop 1
	v_cndmask_b32_e64 v129, v129, v131, s[2:3]
	v_mul_f32_e32 v130, 0x37800000, v129
	v_cndmask_b32_e32 v129, v129, v130, vcc
	v_cmp_class_f32_e32 vcc, v128, v178
	s_nop 1
	v_cndmask_b32_e32 v128, v129, v128, vcc
	v_div_scale_f32 v129, s[2:3], v128, v128, 1.0
	v_rcp_f32_e32 v130, v129
	v_div_scale_f32 v131, vcc, 1.0, v128, 1.0
	v_fma_f32 v132, -v129, v130, 1.0
	v_fmac_f32_e32 v130, v132, v130
	v_mul_f32_e32 v132, v131, v130
	v_fma_f32 v133, -v129, v132, v131
	v_fmac_f32_e32 v132, v133, v130
	v_fma_f32 v129, -v129, v132, v131
	v_div_fmas_f32 v129, v129, v130, v132
	v_div_fixup_f32 v184, v129, v128, 1.0
	s_add_u32 s100, s64, 0x40000
	s_addc_u32 s101, s65, 0
	v_pk_mul_f32 v[220:221], v[92:93], v[184:185] op_sel_hi:[1,0]
	v_pk_mul_f32 v[222:223], v[94:95], v[184:185] op_sel_hi:[1,0]
	v_pk_mul_f32 v[224:225], v[88:89], v[184:185] op_sel_hi:[1,0]
	v_pk_mul_f32 v[226:227], v[90:91], v[184:185] op_sel_hi:[1,0]
	v_pk_mul_f32 v[220:221], v[148:149], v[220:221]
	v_pk_mul_f32 v[222:223], v[150:151], v[222:223]
	v_pk_mul_f32 v[224:225], v[152:153], v[224:225]
	v_pk_mul_f32 v[226:227], v[154:155], v[226:227]
	s_nop 0
	global_store_dwordx4 v185, v[220:223], s[100:101] offset:0
	global_store_dwordx4 v185, v[224:227], s[100:101] offset:16
	v_pk_mul_f32 v[228:229], v[84:85], v[184:185] op_sel_hi:[1,0]
	v_pk_mul_f32 v[230:231], v[86:87], v[184:185] op_sel_hi:[1,0]
	v_pk_mul_f32 v[232:233], v[80:81], v[184:185] op_sel_hi:[1,0]
	v_pk_mul_f32 v[234:235], v[82:83], v[184:185] op_sel_hi:[1,0]
	v_pk_mul_f32 v[228:229], v[156:157], v[228:229]
	v_pk_mul_f32 v[230:231], v[158:159], v[230:231]
	v_pk_mul_f32 v[232:233], v[160:161], v[232:233]
	v_pk_mul_f32 v[234:235], v[162:163], v[234:235]
	s_nop 0
	global_store_dwordx4 v185, v[228:231], s[100:101] offset:512
	global_store_dwordx4 v185, v[232:235], s[100:101] offset:528
	s_waitcnt vmcnt(20)
	v_fmamk_f32 v128, v167, 0x3a000000, v177
	v_mul_f32_e32 v129, 0x4f800000, v128
	v_cmp_gt_f32_e32 vcc, s9, v128
	s_nop 1
	v_cndmask_b32_e32 v128, v128, v129, vcc
	v_sqrt_f32_e32 v129, v128
	s_nop 0
	v_add_u32_e32 v130, -1, v129
	v_add_u32_e32 v131, 1, v129
	v_fma_f32 v132, -v130, v129, v128
	v_fma_f32 v133, -v131, v129, v128
	v_cmp_ge_f32_e64 s[2:3], 0, v132
	s_nop 1
	v_cndmask_b32_e64 v129, v129, v130, s[2:3]
	v_cmp_lt_f32_e64 s[2:3], 0, v133
	s_nop 1
	v_cndmask_b32_e64 v129, v129, v131, s[2:3]
	v_mul_f32_e32 v130, 0x37800000, v129
	v_cndmask_b32_e32 v129, v129, v130, vcc
	v_cmp_class_f32_e32 vcc, v128, v178
	s_nop 1
	v_cndmask_b32_e32 v128, v129, v128, vcc
	v_div_scale_f32 v129, s[2:3], v128, v128, 1.0
	v_rcp_f32_e32 v130, v129
	v_div_scale_f32 v131, vcc, 1.0, v128, 1.0
	v_fma_f32 v132, -v129, v130, 1.0
	v_fmac_f32_e32 v130, v132, v130
	v_mul_f32_e32 v132, v131, v130
	v_fma_f32 v133, -v129, v132, v131
	v_fmac_f32_e32 v132, v133, v130
	v_fma_f32 v129, -v129, v132, v131
	v_div_fmas_f32 v129, v129, v130, v132
	v_div_fixup_f32 v184, v129, v128, 1.0
	s_add_u32 s100, s64, 0x60000
	s_addc_u32 s101, s65, 0
	v_pk_mul_f32 v[236:237], v[76:77], v[184:185] op_sel_hi:[1,0]
	v_pk_mul_f32 v[238:239], v[78:79], v[184:185] op_sel_hi:[1,0]
	v_pk_mul_f32 v[240:241], v[72:73], v[184:185] op_sel_hi:[1,0]
	v_pk_mul_f32 v[242:243], v[74:75], v[184:185] op_sel_hi:[1,0]
	v_pk_mul_f32 v[236:237], v[148:149], v[236:237]
	v_pk_mul_f32 v[238:239], v[150:151], v[238:239]
	v_pk_mul_f32 v[240:241], v[152:153], v[240:241]
	v_pk_mul_f32 v[242:243], v[154:155], v[242:243]
	s_nop 0
	global_store_dwordx4 v185, v[236:239], s[100:101] offset:0
	global_store_dwordx4 v185, v[240:243], s[100:101] offset:16
	v_pk_mul_f32 v[244:245], v[68:69], v[184:185] op_sel_hi:[1,0]
	v_pk_mul_f32 v[246:247], v[70:71], v[184:185] op_sel_hi:[1,0]
	v_pk_mul_f32 v[248:249], v[64:65], v[184:185] op_sel_hi:[1,0]
	v_pk_mul_f32 v[250:251], v[66:67], v[184:185] op_sel_hi:[1,0]
	v_pk_mul_f32 v[244:245], v[156:157], v[244:245]
	v_pk_mul_f32 v[246:247], v[158:159], v[246:247]
	v_pk_mul_f32 v[248:249], v[160:161], v[248:249]
	v_pk_mul_f32 v[250:251], v[162:163], v[250:251]
	s_nop 0
	global_store_dwordx4 v185, v[244:247], s[100:101] offset:512
	global_store_dwordx4 v185, v[248:251], s[100:101] offset:528
	s_waitcnt vmcnt(23)
	v_fmamk_f32 v128, v168, 0x3a000000, v177
	v_mul_f32_e32 v129, 0x4f800000, v128
	v_cmp_gt_f32_e32 vcc, s9, v128
	s_nop 1
	v_cndmask_b32_e32 v128, v128, v129, vcc
	v_sqrt_f32_e32 v129, v128
	s_nop 0
	v_add_u32_e32 v130, -1, v129
	v_add_u32_e32 v131, 1, v129
	v_fma_f32 v132, -v130, v129, v128
	v_fma_f32 v133, -v131, v129, v128
	v_cmp_ge_f32_e64 s[2:3], 0, v132
	s_nop 1
	v_cndmask_b32_e64 v129, v129, v130, s[2:3]
	v_cmp_lt_f32_e64 s[2:3], 0, v133
	s_nop 1
	v_cndmask_b32_e64 v129, v129, v131, s[2:3]
	v_mul_f32_e32 v130, 0x37800000, v129
	v_cndmask_b32_e32 v129, v129, v130, vcc
	v_cmp_class_f32_e32 vcc, v128, v178
	s_nop 1
	v_cndmask_b32_e32 v128, v129, v128, vcc
	v_div_scale_f32 v129, s[2:3], v128, v128, 1.0
	v_rcp_f32_e32 v130, v129
	v_div_scale_f32 v131, vcc, 1.0, v128, 1.0
	v_fma_f32 v132, -v129, v130, 1.0
	v_fmac_f32_e32 v130, v132, v130
	v_mul_f32_e32 v132, v131, v130
	v_fma_f32 v133, -v129, v132, v131
	v_fmac_f32_e32 v132, v133, v130
	v_fma_f32 v129, -v129, v132, v131
	v_div_fmas_f32 v129, v129, v130, v132
	v_div_fixup_f32 v184, v129, v128, 1.0
	s_add_u32 s100, s64, 0x100000
	s_addc_u32 s101, s65, 0
	v_pk_mul_f32 v[188:189], v[60:61], v[184:185] op_sel_hi:[1,0]
	v_pk_mul_f32 v[190:191], v[62:63], v[184:185] op_sel_hi:[1,0]
	v_pk_mul_f32 v[192:193], v[56:57], v[184:185] op_sel_hi:[1,0]
	v_pk_mul_f32 v[194:195], v[58:59], v[184:185] op_sel_hi:[1,0]
	v_pk_mul_f32 v[188:189], v[148:149], v[188:189]
	v_pk_mul_f32 v[190:191], v[150:151], v[190:191]
	v_pk_mul_f32 v[192:193], v[152:153], v[192:193]
	v_pk_mul_f32 v[194:195], v[154:155], v[194:195]
	s_nop 0
	global_store_dwordx4 v185, v[188:191], s[100:101] offset:0
	global_store_dwordx4 v185, v[192:195], s[100:101] offset:16
	v_pk_mul_f32 v[196:197], v[52:53], v[184:185] op_sel_hi:[1,0]
	v_pk_mul_f32 v[198:199], v[54:55], v[184:185] op_sel_hi:[1,0]
	v_pk_mul_f32 v[200:201], v[48:49], v[184:185] op_sel_hi:[1,0]
	v_pk_mul_f32 v[202:203], v[50:51], v[184:185] op_sel_hi:[1,0]
	v_pk_mul_f32 v[196:197], v[156:157], v[196:197]
	v_pk_mul_f32 v[198:199], v[158:159], v[198:199]
	v_pk_mul_f32 v[200:201], v[160:161], v[200:201]
	v_pk_mul_f32 v[202:203], v[162:163], v[202:203]
	s_nop 0
	global_store_dwordx4 v185, v[196:199], s[100:101] offset:512
	global_store_dwordx4 v185, v[200:203], s[100:101] offset:528
	s_waitcnt vmcnt(26)
	v_fmamk_f32 v128, v169, 0x3a000000, v177
	v_mul_f32_e32 v129, 0x4f800000, v128
	v_cmp_gt_f32_e32 vcc, s9, v128
	s_nop 1
	v_cndmask_b32_e32 v128, v128, v129, vcc
	v_sqrt_f32_e32 v129, v128
	s_nop 0
	v_add_u32_e32 v130, -1, v129
	v_add_u32_e32 v131, 1, v129
	v_fma_f32 v132, -v130, v129, v128
	v_fma_f32 v133, -v131, v129, v128
	v_cmp_ge_f32_e64 s[2:3], 0, v132
	s_nop 1
	v_cndmask_b32_e64 v129, v129, v130, s[2:3]
	v_cmp_lt_f32_e64 s[2:3], 0, v133
	s_nop 1
	v_cndmask_b32_e64 v129, v129, v131, s[2:3]
	v_mul_f32_e32 v130, 0x37800000, v129
	v_cndmask_b32_e32 v129, v129, v130, vcc
	v_cmp_class_f32_e32 vcc, v128, v178
	s_nop 1
	v_cndmask_b32_e32 v128, v129, v128, vcc
	v_div_scale_f32 v129, s[2:3], v128, v128, 1.0
	v_rcp_f32_e32 v130, v129
	v_div_scale_f32 v131, vcc, 1.0, v128, 1.0
	v_fma_f32 v132, -v129, v130, 1.0
	v_fmac_f32_e32 v130, v132, v130
	v_mul_f32_e32 v132, v131, v130
	v_fma_f32 v133, -v129, v132, v131
	v_fmac_f32_e32 v132, v133, v130
	v_fma_f32 v129, -v129, v132, v131
	v_div_fmas_f32 v129, v129, v130, v132
	v_div_fixup_f32 v184, v129, v128, 1.0
	s_add_u32 s100, s64, 0x120000
	s_addc_u32 s101, s65, 0
	v_pk_mul_f32 v[204:205], v[44:45], v[184:185] op_sel_hi:[1,0]
	v_pk_mul_f32 v[206:207], v[46:47], v[184:185] op_sel_hi:[1,0]
	v_pk_mul_f32 v[208:209], v[40:41], v[184:185] op_sel_hi:[1,0]
	v_pk_mul_f32 v[210:211], v[42:43], v[184:185] op_sel_hi:[1,0]
	v_pk_mul_f32 v[204:205], v[148:149], v[204:205]
	v_pk_mul_f32 v[206:207], v[150:151], v[206:207]
	v_pk_mul_f32 v[208:209], v[152:153], v[208:209]
	v_pk_mul_f32 v[210:211], v[154:155], v[210:211]
	s_nop 0
	global_store_dwordx4 v185, v[204:207], s[100:101] offset:0
	global_store_dwordx4 v185, v[208:211], s[100:101] offset:16
	v_pk_mul_f32 v[212:213], v[36:37], v[184:185] op_sel_hi:[1,0]
	v_pk_mul_f32 v[214:215], v[38:39], v[184:185] op_sel_hi:[1,0]
	v_pk_mul_f32 v[216:217], v[32:33], v[184:185] op_sel_hi:[1,0]
	v_pk_mul_f32 v[218:219], v[34:35], v[184:185] op_sel_hi:[1,0]
	v_pk_mul_f32 v[212:213], v[156:157], v[212:213]
	v_pk_mul_f32 v[214:215], v[158:159], v[214:215]
	v_pk_mul_f32 v[216:217], v[160:161], v[216:217]
	v_pk_mul_f32 v[218:219], v[162:163], v[218:219]
	s_nop 0
	global_store_dwordx4 v185, v[212:215], s[100:101] offset:512
	global_store_dwordx4 v185, v[216:219], s[100:101] offset:528
	s_waitcnt vmcnt(29)
	v_fmamk_f32 v128, v170, 0x3a000000, v177
	v_mul_f32_e32 v129, 0x4f800000, v128
	v_cmp_gt_f32_e32 vcc, s9, v128
	s_nop 1
	v_cndmask_b32_e32 v128, v128, v129, vcc
	v_sqrt_f32_e32 v129, v128
	s_nop 0
	v_add_u32_e32 v130, -1, v129
	v_add_u32_e32 v131, 1, v129
	v_fma_f32 v132, -v130, v129, v128
	v_fma_f32 v133, -v131, v129, v128
	v_cmp_ge_f32_e64 s[2:3], 0, v132
	s_nop 1
	v_cndmask_b32_e64 v129, v129, v130, s[2:3]
	v_cmp_lt_f32_e64 s[2:3], 0, v133
	s_nop 1
	v_cndmask_b32_e64 v129, v129, v131, s[2:3]
	v_mul_f32_e32 v130, 0x37800000, v129
	v_cndmask_b32_e32 v129, v129, v130, vcc
	v_cmp_class_f32_e32 vcc, v128, v178
	s_nop 1
	v_cndmask_b32_e32 v128, v129, v128, vcc
	v_div_scale_f32 v129, s[2:3], v128, v128, 1.0
	v_rcp_f32_e32 v130, v129
	v_div_scale_f32 v131, vcc, 1.0, v128, 1.0
	v_fma_f32 v132, -v129, v130, 1.0
	v_fmac_f32_e32 v130, v132, v130
	v_mul_f32_e32 v132, v131, v130
	v_fma_f32 v133, -v129, v132, v131
	v_fmac_f32_e32 v132, v133, v130
	v_fma_f32 v129, -v129, v132, v131
	v_div_fmas_f32 v129, v129, v130, v132
	v_div_fixup_f32 v184, v129, v128, 1.0
	s_add_u32 s100, s64, 0x140000
	s_addc_u32 s101, s65, 0
	v_pk_mul_f32 v[220:221], v[28:29], v[184:185] op_sel_hi:[1,0]
	v_pk_mul_f32 v[222:223], v[30:31], v[184:185] op_sel_hi:[1,0]
	v_pk_mul_f32 v[224:225], v[24:25], v[184:185] op_sel_hi:[1,0]
	v_pk_mul_f32 v[226:227], v[26:27], v[184:185] op_sel_hi:[1,0]
	v_pk_mul_f32 v[220:221], v[148:149], v[220:221]
	v_pk_mul_f32 v[222:223], v[150:151], v[222:223]
	v_pk_mul_f32 v[224:225], v[152:153], v[224:225]
	v_pk_mul_f32 v[226:227], v[154:155], v[226:227]
	s_nop 0
	global_store_dwordx4 v185, v[220:223], s[100:101] offset:0
	global_store_dwordx4 v185, v[224:227], s[100:101] offset:16
	v_pk_mul_f32 v[228:229], v[20:21], v[184:185] op_sel_hi:[1,0]
	v_pk_mul_f32 v[230:231], v[22:23], v[184:185] op_sel_hi:[1,0]
	v_pk_mul_f32 v[232:233], v[16:17], v[184:185] op_sel_hi:[1,0]
	v_pk_mul_f32 v[234:235], v[18:19], v[184:185] op_sel_hi:[1,0]
	v_pk_mul_f32 v[228:229], v[156:157], v[228:229]
	v_pk_mul_f32 v[230:231], v[158:159], v[230:231]
	v_pk_mul_f32 v[232:233], v[160:161], v[232:233]
	v_pk_mul_f32 v[234:235], v[162:163], v[234:235]
	s_nop 0
	global_store_dwordx4 v185, v[228:231], s[100:101] offset:512
	global_store_dwordx4 v185, v[232:235], s[100:101] offset:528
	s_waitcnt vmcnt(32)
	v_fmamk_f32 v128, v171, 0x3a000000, v177
	v_mul_f32_e32 v129, 0x4f800000, v128
	v_cmp_gt_f32_e32 vcc, s9, v128
	s_nop 1
	v_cndmask_b32_e32 v128, v128, v129, vcc
	v_sqrt_f32_e32 v129, v128
	s_nop 0
	v_add_u32_e32 v130, -1, v129
	v_add_u32_e32 v131, 1, v129
	v_fma_f32 v132, -v130, v129, v128
	v_fma_f32 v133, -v131, v129, v128
	v_cmp_ge_f32_e64 s[2:3], 0, v132
	s_nop 1
	v_cndmask_b32_e64 v129, v129, v130, s[2:3]
	v_cmp_lt_f32_e64 s[2:3], 0, v133
	s_nop 1
	v_cndmask_b32_e64 v129, v129, v131, s[2:3]
	v_mul_f32_e32 v130, 0x37800000, v129
	v_cndmask_b32_e32 v129, v129, v130, vcc
	v_cmp_class_f32_e32 vcc, v128, v178
	s_nop 1
	v_cndmask_b32_e32 v128, v129, v128, vcc
	v_div_scale_f32 v129, s[2:3], v128, v128, 1.0
	v_rcp_f32_e32 v130, v129
	v_div_scale_f32 v131, vcc, 1.0, v128, 1.0
	v_fma_f32 v132, -v129, v130, 1.0
	v_fmac_f32_e32 v130, v132, v130
	v_mul_f32_e32 v132, v131, v130
	v_fma_f32 v133, -v129, v132, v131
	v_fmac_f32_e32 v132, v133, v130
	v_fma_f32 v129, -v129, v132, v131
	v_div_fmas_f32 v129, v129, v130, v132
	v_div_fixup_f32 v184, v129, v128, 1.0
	s_add_u32 s100, s64, 0x160000
	s_addc_u32 s101, s65, 0
	v_pk_mul_f32 v[236:237], v[12:13], v[184:185] op_sel_hi:[1,0]
	v_pk_mul_f32 v[238:239], v[14:15], v[184:185] op_sel_hi:[1,0]
	v_pk_mul_f32 v[240:241], v[8:9], v[184:185] op_sel_hi:[1,0]
	v_pk_mul_f32 v[242:243], v[10:11], v[184:185] op_sel_hi:[1,0]
	v_pk_mul_f32 v[236:237], v[148:149], v[236:237]
	v_pk_mul_f32 v[238:239], v[150:151], v[238:239]
	v_pk_mul_f32 v[240:241], v[152:153], v[240:241]
	v_pk_mul_f32 v[242:243], v[154:155], v[242:243]
	s_nop 0
	global_store_dwordx4 v185, v[236:239], s[100:101] offset:0
	global_store_dwordx4 v185, v[240:243], s[100:101] offset:16
	v_pk_mul_f32 v[244:245], v[4:5], v[184:185] op_sel_hi:[1,0]
	v_pk_mul_f32 v[246:247], v[6:7], v[184:185] op_sel_hi:[1,0]
	v_pk_mul_f32 v[248:249], v[0:1], v[184:185] op_sel_hi:[1,0]
	v_pk_mul_f32 v[250:251], v[2:3], v[184:185] op_sel_hi:[1,0]
	v_pk_mul_f32 v[244:245], v[156:157], v[244:245]
	v_pk_mul_f32 v[246:247], v[158:159], v[246:247]
	v_pk_mul_f32 v[248:249], v[160:161], v[248:249]
	v_pk_mul_f32 v[250:251], v[162:163], v[250:251]
	s_nop 0
	global_store_dwordx4 v185, v[244:247], s[100:101] offset:512
	global_store_dwordx4 v185, v[248:251], s[100:101] offset:528
	s_andn2_b64 vcc, exec, s[22:23]
	s_mov_b64 s[2:3], -1
	s_cbranch_vccnz .LBB0_672
	s_and_b64 vcc, exec, s[0:1]
	s_cbranch_vccnz .LBB0_671
	s_barrier
	s_branch .LBB0_671
